# P5/P8: leading half's alignment barrier moved below the epilogue's initial load issue (its first residual/gate loads go out under the trailing half's last MFMA block)
# baseline (speedup 1.0000x reference)
; __device__ __forceinline__ unsigned cvt_pk_bf16(float lo, float hi) { unsigned r; asm volatile("v_cvt_pk_bf16_f32 %0, %1, %2" : "=v"(r) : "v"(lo), "v"(hi)); return r; }
;     __device__ __forceinline__ void operator()(const f32x4 (&acc)[2][2][4][2], const Unit& u, int wr, int wc, int fr, int fq) const {
;         const int row0 = u.pm * BM + wr * 64 + fr, col0 = u.pn * BM + wc * 32 + 4 * fq, b = (u.pm * BM) >> 12;
;         f32x4 gv[2][2], Gv[2][2];
; #pragma unroll
;         for (int bj = 0; bj < 2; ++bj)
; #pragma unroll
;             for (int n = 0; n < 2; ++n) { const int c = col0 + bj * HALF + n * 16; gv[bj][n] = *(const f32x4*)(mod + (size_t)b * 12288 + 2 * 2048 + c);
;                 Gv[bj][n] = *(const f32x4*)(g2 + c) * (*(const f32x4*)(mod + (size_t)b * 12288 + 4 * 2048 + c) + 1.0f); }
;         float* prow = part + (size_t)(u.pn * 4 + wc) * 16384;
; #pragma unroll
;         for (int ai = 0; ai < 2; ++ai)
; #pragma unroll
;             for (int m = 0; m < 4; ++m) { const int row = row0 + ai * HALF + m * 16; const size_t off = (size_t)row * 2048 + col0; float ss = 0.f;
; #pragma unroll
;                 for (int bj = 0; bj < 2; ++bj)
; #pragma unroll
;                     for (int n = 0; n < 2; ++n) { const f32x4 bs = __builtin_nontemporal_load((const f32x4*)(base + off + bj * HALF + n * 16)); const f32x4 x1 = bs + gv[bj][n] * acc[ai][bj][m][n];
;                         *(f32x4*)(out + off + bj * HALF + n * 16) = x1; ss += (x1.x * x1.x + x1.y * x1.y) + (x1.z * x1.z + x1.w * x1.w);
;                         const f32x4 hh = x1 * Gv[bj][n]; u32x2 w; w.x = cvt_pk_bf16(hh.x, hh.y); w.y = cvt_pk_bf16(hh.z, hh.w); *(u32x2*)(A2 + off + bj * HALF + n * 16) = w; }
.LBB0_897:
	v_readlane_b32 s98, v236, 7
	v_readlane_b32 s99, v236, 8
	v_readlane_b32 s76, v236, 35
	v_readlane_b32 s77, v236, 36
	s_ashr_i32 s25, s36, 4
	s_mul_hi_i32 s27, s25, 0xc000
	s_mul_i32 s25, s25, 0xc000
	s_add_u32 s38, s68, s25
	s_addc_u32 s39, s69, s27
	s_add_u32 s40, s38, 0x8000
	s_addc_u32 s41, s39, 0
	s_add_u32 s38, s38, 0x4000
	s_addc_u32 s39, s39, 0
	v_lshl_add_u32 v164, s36, 8, v166
	v_lshl_or_b32 v165, s34, 8, v168
	v_lshlrev_b32_e32 v173, 2, v165
	v_xor_b32_e32 v216, 16, v172
	v_xor_b32_e32 v217, 32, v172
	v_lshlrev_b32_e32 v216, 2, v216
	v_lshlrev_b32_e32 v217, 2, v217
	global_load_dwordx4 v[72:75], v173, s[38:39]
	global_load_dwordx4 v[84:87], v173, s[38:39] offset:64
	global_load_dwordx4 v[92:95], v173, s[38:39] offset:512
	global_load_dwordx4 v[96:99], v173, s[38:39] offset:576
	global_load_dwordx4 v[156:159], v173, s[40:41]
	global_load_dwordx4 v[160:163], v173, s[40:41] offset:64
	global_load_dwordx4 v[174:177], v173, s[40:41] offset:512
	global_load_dwordx4 v[178:181], v173, s[40:41] offset:576
	global_load_dwordx4 v[182:185], v173, s[76:77]
	global_load_dwordx4 v[188:191], v173, s[76:77] offset:64
	global_load_dwordx4 v[192:195], v173, s[76:77] offset:512
	global_load_dwordx4 v[196:199], v173, s[76:77] offset:576
	v_lshl_add_u32 v164, v164, 13, v173
	v_mov_b32_e32 v165, v164
	v_lshrrev_b32_e32 v173, 1, v164
	global_load_dwordx4 v[200:203], v164, s[98:99] nt
	global_load_dwordx4 v[204:207], v164, s[98:99] offset:64 nt
	global_load_dwordx4 v[208:211], v164, s[98:99] offset:512 nt
	global_load_dwordx4 v[212:215], v164, s[98:99] offset:576 nt
	v_add_u32_e32 v164, 0x20000, v164
	s_and_b64 vcc, exec, s[14:15]
	s_cbranch_vccz .Lalignmv_p5
	s_barrier
.Lalignmv_p5:
	s_waitcnt vmcnt(4)
	v_pk_add_f32 v[156:157], v[156:157], 1.0 op_sel_hi:[1,0]
	v_pk_add_f32 v[158:159], v[158:159], 1.0 op_sel_hi:[1,0]
	v_pk_mul_f32 v[182:183], v[182:183], v[156:157]
	v_pk_mul_f32 v[184:185], v[184:185], v[158:159]
	v_pk_add_f32 v[160:161], v[160:161], 1.0 op_sel_hi:[1,0]
	v_pk_add_f32 v[162:163], v[162:163], 1.0 op_sel_hi:[1,0]
	v_pk_mul_f32 v[188:189], v[188:189], v[160:161]
	v_pk_mul_f32 v[190:191], v[190:191], v[162:163]
	v_pk_add_f32 v[174:175], v[174:175], 1.0 op_sel_hi:[1,0]
	v_pk_add_f32 v[176:177], v[176:177], 1.0 op_sel_hi:[1,0]
	v_pk_mul_f32 v[192:193], v[192:193], v[174:175]
	v_pk_mul_f32 v[194:195], v[194:195], v[176:177]
	v_pk_add_f32 v[178:179], v[178:179], 1.0 op_sel_hi:[1,0]
	v_pk_add_f32 v[180:181], v[180:181], 1.0 op_sel_hi:[1,0]
	v_pk_mul_f32 v[196:197], v[196:197], v[178:179]
	v_pk_mul_f32 v[198:199], v[198:199], v[180:181]
	global_load_dwordx4 v[156:159], v164, s[98:99] nt
	global_load_dwordx4 v[160:163], v164, s[98:99] offset:64 nt
	global_load_dwordx4 v[174:177], v164, s[98:99] offset:512 nt
	global_load_dwordx4 v[178:181], v164, s[98:99] offset:576 nt
	v_add_u32_e32 v164, 0x20000, v164
	s_waitcnt vmcnt(7)
	v_pk_fma_f32 v[200:201], v[140:141], v[72:73], v[200:201]
	v_pk_fma_f32 v[202:203], v[142:143], v[74:75], v[202:203]
	global_store_dwordx4 v165, v[200:203], s[66:67]
	v_pk_mul_f32 v[140:141], v[200:201], v[182:183]
	v_pk_mul_f32 v[142:143], v[202:203], v[184:185]
	v_cvt_pk_bf16_f32 v140, v140, v141
	v_cvt_pk_bf16_f32 v141, v142, v143
	global_store_dwordx2 v173, v[140:141], s[8:9]
	v_mul_f32_e32 v142, v200, v200
	v_fmac_f32_e32 v142, v201, v201
	v_fmac_f32_e32 v142, v202, v202
	v_fmac_f32_e32 v142, v203, v203
	global_load_dwordx4 v[200:203], v164, s[98:99] nt
	s_waitcnt vmcnt(9)
	v_pk_fma_f32 v[204:205], v[136:137], v[84:85], v[204:205]
	v_pk_fma_f32 v[206:207], v[138:139], v[86:87], v[206:207]
	global_store_dwordx4 v165, v[204:207], s[66:67] offset:64
	v_pk_mul_f32 v[136:137], v[204:205], v[188:189]
	v_pk_mul_f32 v[138:139], v[206:207], v[190:191]
	v_cvt_pk_bf16_f32 v136, v136, v137
	v_cvt_pk_bf16_f32 v137, v138, v139
	global_store_dwordx2 v173, v[136:137], s[8:9] offset:32
	v_fmac_f32_e32 v142, v204, v204
	v_fmac_f32_e32 v142, v205, v205
	v_fmac_f32_e32 v142, v206, v206
	v_fmac_f32_e32 v142, v207, v207
	global_load_dwordx4 v[204:207], v164, s[98:99] offset:64 nt
	s_waitcnt vmcnt(11)
	v_pk_fma_f32 v[208:209], v[132:133], v[92:93], v[208:209]
	v_pk_fma_f32 v[210:211], v[134:135], v[94:95], v[210:211]
	global_store_dwordx4 v165, v[208:211], s[66:67] offset:512
	v_pk_mul_f32 v[132:133], v[208:209], v[192:193]
	v_pk_mul_f32 v[134:135], v[210:211], v[194:195]
	v_cvt_pk_bf16_f32 v132, v132, v133
	v_cvt_pk_bf16_f32 v133, v134, v135
	global_store_dwordx2 v173, v[132:133], s[8:9] offset:256
	v_fmac_f32_e32 v142, v208, v208
	v_fmac_f32_e32 v142, v209, v209
	v_fmac_f32_e32 v142, v210, v210
	v_fmac_f32_e32 v142, v211, v211
	global_load_dwordx4 v[208:211], v164, s[98:99] offset:512 nt
	s_waitcnt vmcnt(13)
	v_pk_fma_f32 v[212:213], v[128:129], v[96:97], v[212:213]
	v_pk_fma_f32 v[214:215], v[130:131], v[98:99], v[214:215]
	global_store_dwordx4 v165, v[212:215], s[66:67] offset:576
	v_pk_mul_f32 v[128:129], v[212:213], v[196:197]
	v_pk_mul_f32 v[130:131], v[214:215], v[198:199]
	v_cvt_pk_bf16_f32 v128, v128, v129
	v_cvt_pk_bf16_f32 v129, v130, v131
	global_store_dwordx2 v173, v[128:129], s[8:9] offset:288
	v_fmac_f32_e32 v142, v212, v212
	v_fmac_f32_e32 v142, v213, v213
	v_fmac_f32_e32 v142, v214, v214
	v_fmac_f32_e32 v142, v215, v215
	v_add_u32_e32 v165, 0x20000, v165
	v_lshrrev_b32_e32 v173, 1, v165
	global_load_dwordx4 v[212:215], v164, s[98:99] offset:576 nt
	v_add_u32_e32 v164, 0x20000, v164
	s_waitcnt vmcnt(15)
; __device__ __forceinline__ unsigned cvt_pk_bf16(float lo, float hi) { unsigned r; asm volatile("v_cvt_pk_bf16_f32 %0, %1, %2" : "=v"(r) : "v"(lo), "v"(hi)); return r; }
;     __device__ __forceinline__ void operator()(const f32x4 (&acc)[2][2][4][2], const Unit& u, int wr, int wc, int fr, int fq) const {
;     ...
;             for (int m = 0; m < 4; ++m) { const int row = row0 + ai * HALF + m * 16; const size_t off = (size_t)row * 2048 + col0; float ss = 0.f;
; #pragma unroll
;                 for (int bj = 0; bj < 2; ++bj)
; #pragma unroll
;                     for (int n = 0; n < 2; ++n) { const f32x4 bs = __builtin_nontemporal_load((const f32x4*)(base + off + bj * HALF + n * 16)); const f32x4 x1 = bs + gv[bj][n] * acc[ai][bj][m][n];
;                         *(f32x4*)(out + off + bj * HALF + n * 16) = x1; ss += (x1.x * x1.x + x1.y * x1.y) + (x1.z * x1.z + x1.w * x1.w);
;                         const f32x4 hh = x1 * Gv[bj][n]; u32x2 w; w.x = cvt_pk_bf16(hh.x, hh.y); w.y = cvt_pk_bf16(hh.z, hh.w); *(u32x2*)(A2 + off + bj * HALF + n * 16) = w; }
	v_pk_fma_f32 v[156:157], v[124:125], v[72:73], v[156:157]
	v_pk_fma_f32 v[158:159], v[126:127], v[74:75], v[158:159]
	global_store_dwordx4 v165, v[156:159], s[66:67]
	v_pk_mul_f32 v[124:125], v[156:157], v[182:183]
	v_pk_mul_f32 v[126:127], v[158:159], v[184:185]
	v_cvt_pk_bf16_f32 v124, v124, v125
	v_cvt_pk_bf16_f32 v125, v126, v127
	global_store_dwordx2 v173, v[124:125], s[8:9]
	v_mul_f32_e32 v126, v156, v156
	v_fmac_f32_e32 v126, v157, v157
	v_fmac_f32_e32 v126, v158, v158
	v_fmac_f32_e32 v126, v159, v159
	global_load_dwordx4 v[156:159], v164, s[98:99] nt
	s_waitcnt vmcnt(17)
	v_pk_fma_f32 v[160:161], v[120:121], v[84:85], v[160:161]
	v_pk_fma_f32 v[162:163], v[122:123], v[86:87], v[162:163]
	global_store_dwordx4 v165, v[160:163], s[66:67] offset:64
	v_pk_mul_f32 v[120:121], v[160:161], v[188:189]
	v_pk_mul_f32 v[122:123], v[162:163], v[190:191]
	v_cvt_pk_bf16_f32 v120, v120, v121
	v_cvt_pk_bf16_f32 v121, v122, v123
	global_store_dwordx2 v173, v[120:121], s[8:9] offset:32
	v_fmac_f32_e32 v126, v160, v160
	v_fmac_f32_e32 v126, v161, v161
	v_fmac_f32_e32 v126, v162, v162
	v_fmac_f32_e32 v126, v163, v163
	global_load_dwordx4 v[160:163], v164, s[98:99] offset:64 nt
	s_waitcnt vmcnt(19)
	v_pk_fma_f32 v[174:175], v[116:117], v[92:93], v[174:175]
	v_pk_fma_f32 v[176:177], v[118:119], v[94:95], v[176:177]
	global_store_dwordx4 v165, v[174:177], s[66:67] offset:512
	v_pk_mul_f32 v[116:117], v[174:175], v[192:193]
	v_pk_mul_f32 v[118:119], v[176:177], v[194:195]
	v_cvt_pk_bf16_f32 v116, v116, v117
	v_cvt_pk_bf16_f32 v117, v118, v119
	global_store_dwordx2 v173, v[116:117], s[8:9] offset:256
	v_fmac_f32_e32 v126, v174, v174
	v_fmac_f32_e32 v126, v175, v175
	v_fmac_f32_e32 v126, v176, v176
	v_fmac_f32_e32 v126, v177, v177
	global_load_dwordx4 v[174:177], v164, s[98:99] offset:512 nt
	s_waitcnt vmcnt(21)
	v_pk_fma_f32 v[178:179], v[112:113], v[96:97], v[178:179]
	v_pk_fma_f32 v[180:181], v[114:115], v[98:99], v[180:181]
	global_store_dwordx4 v165, v[178:181], s[66:67] offset:576
	v_pk_mul_f32 v[112:113], v[178:179], v[196:197]
	v_pk_mul_f32 v[114:115], v[180:181], v[198:199]
	v_cvt_pk_bf16_f32 v112, v112, v113
	v_cvt_pk_bf16_f32 v113, v114, v115
	global_store_dwordx2 v173, v[112:113], s[8:9] offset:288
	v_fmac_f32_e32 v126, v178, v178
	v_fmac_f32_e32 v126, v179, v179
	v_fmac_f32_e32 v126, v180, v180
	v_fmac_f32_e32 v126, v181, v181
	v_add_u32_e32 v165, 0x20000, v165
	v_lshrrev_b32_e32 v173, 1, v165
	global_load_dwordx4 v[178:181], v164, s[98:99] offset:576 nt
	v_add_u32_e32 v164, 0xa0000, v164
	s_waitcnt vmcnt(21)
	v_pk_fma_f32 v[200:201], v[108:109], v[72:73], v[200:201]
	v_pk_fma_f32 v[202:203], v[110:111], v[74:75], v[202:203]
	global_store_dwordx4 v165, v[200:203], s[66:67]
	v_pk_mul_f32 v[108:109], v[200:201], v[182:183]
	v_pk_mul_f32 v[110:111], v[202:203], v[184:185]
	v_cvt_pk_bf16_f32 v108, v108, v109
	v_cvt_pk_bf16_f32 v109, v110, v111
	global_store_dwordx2 v173, v[108:109], s[8:9]
	v_mul_f32_e32 v110, v200, v200
	v_fmac_f32_e32 v110, v201, v201
	v_fmac_f32_e32 v110, v202, v202
	v_fmac_f32_e32 v110, v203, v203
	global_load_dwordx4 v[200:203], v164, s[98:99] nt
	s_waitcnt vmcnt(21)
	v_pk_fma_f32 v[204:205], v[104:105], v[84:85], v[204:205]
	v_pk_fma_f32 v[206:207], v[106:107], v[86:87], v[206:207]
	global_store_dwordx4 v165, v[204:207], s[66:67] offset:64
	v_pk_mul_f32 v[104:105], v[204:205], v[188:189]
	v_pk_mul_f32 v[106:107], v[206:207], v[190:191]
	v_cvt_pk_bf16_f32 v104, v104, v105
	v_cvt_pk_bf16_f32 v105, v106, v107
	global_store_dwordx2 v173, v[104:105], s[8:9] offset:32
	v_fmac_f32_e32 v110, v204, v204
	v_fmac_f32_e32 v110, v205, v205
	v_fmac_f32_e32 v110, v206, v206
	v_fmac_f32_e32 v110, v207, v207
	global_load_dwordx4 v[204:207], v164, s[98:99] offset:64 nt
	s_waitcnt vmcnt(21)
	v_pk_fma_f32 v[208:209], v[100:101], v[92:93], v[208:209]
	v_pk_fma_f32 v[210:211], v[102:103], v[94:95], v[210:211]
	global_store_dwordx4 v165, v[208:211], s[66:67] offset:512
	v_pk_mul_f32 v[100:101], v[208:209], v[192:193]
	v_pk_mul_f32 v[102:103], v[210:211], v[194:195]
	v_cvt_pk_bf16_f32 v100, v100, v101
	v_cvt_pk_bf16_f32 v101, v102, v103
	global_store_dwordx2 v173, v[100:101], s[8:9] offset:256
	v_fmac_f32_e32 v110, v208, v208
	v_fmac_f32_e32 v110, v209, v209
	v_fmac_f32_e32 v110, v210, v210
	v_fmac_f32_e32 v110, v211, v211
	global_load_dwordx4 v[208:211], v164, s[98:99] offset:512 nt
	s_waitcnt vmcnt(21)
	v_pk_fma_f32 v[212:213], v[88:89], v[96:97], v[212:213]
	v_pk_fma_f32 v[214:215], v[90:91], v[98:99], v[214:215]
	global_store_dwordx4 v165, v[212:215], s[66:67] offset:576
	v_pk_mul_f32 v[88:89], v[212:213], v[196:197]
	v_pk_mul_f32 v[90:91], v[214:215], v[198:199]
	v_cvt_pk_bf16_f32 v88, v88, v89
	v_cvt_pk_bf16_f32 v89, v90, v91
	global_store_dwordx2 v173, v[88:89], s[8:9] offset:288
	v_fmac_f32_e32 v110, v212, v212
	v_fmac_f32_e32 v110, v213, v213
	v_fmac_f32_e32 v110, v214, v214
	v_fmac_f32_e32 v110, v215, v215
	v_add_u32_e32 v165, 0x20000, v165
	v_lshrrev_b32_e32 v173, 1, v165
	global_load_dwordx4 v[212:215], v164, s[98:99] offset:576 nt
	v_add_u32_e32 v164, 0x20000, v164
	s_waitcnt vmcnt(21)
	v_pk_fma_f32 v[156:157], v[80:81], v[72:73], v[156:157]
	v_pk_fma_f32 v[158:159], v[82:83], v[74:75], v[158:159]
	global_store_dwordx4 v165, v[156:159], s[66:67]
	v_pk_mul_f32 v[80:81], v[156:157], v[182:183]
	v_pk_mul_f32 v[82:83], v[158:159], v[184:185]
	v_cvt_pk_bf16_f32 v80, v80, v81
	v_cvt_pk_bf16_f32 v81, v82, v83
	global_store_dwordx2 v173, v[80:81], s[8:9]
	v_mul_f32_e32 v82, v156, v156
	v_fmac_f32_e32 v82, v157, v157
	v_fmac_f32_e32 v82, v158, v158
	v_fmac_f32_e32 v82, v159, v159
	global_load_dwordx4 v[156:159], v164, s[98:99] nt
	s_waitcnt vmcnt(21)
; __device__ __forceinline__ unsigned cvt_pk_bf16(float lo, float hi) { unsigned r; asm volatile("v_cvt_pk_bf16_f32 %0, %1, %2" : "=v"(r) : "v"(lo), "v"(hi)); return r; }
;     __device__ __forceinline__ void operator()(const f32x4 (&acc)[2][2][4][2], const Unit& u, int wr, int wc, int fr, int fq) const {
;     ...
;             for (int m = 0; m < 4; ++m) { const int row = row0 + ai * HALF + m * 16; const size_t off = (size_t)row * 2048 + col0; float ss = 0.f;
; #pragma unroll
;                 for (int bj = 0; bj < 2; ++bj)
; #pragma unroll
;                     for (int n = 0; n < 2; ++n) { const f32x4 bs = __builtin_nontemporal_load((const f32x4*)(base + off + bj * HALF + n * 16)); const f32x4 x1 = bs + gv[bj][n] * acc[ai][bj][m][n];
;                         *(f32x4*)(out + off + bj * HALF + n * 16) = x1; ss += (x1.x * x1.x + x1.y * x1.y) + (x1.z * x1.z + x1.w * x1.w);
;                         const f32x4 hh = x1 * Gv[bj][n]; u32x2 w; w.x = cvt_pk_bf16(hh.x, hh.y); w.y = cvt_pk_bf16(hh.z, hh.w); *(u32x2*)(A2 + off + bj * HALF + n * 16) = w; }
	v_pk_fma_f32 v[160:161], v[76:77], v[84:85], v[160:161]
	v_pk_fma_f32 v[162:163], v[78:79], v[86:87], v[162:163]
	global_store_dwordx4 v165, v[160:163], s[66:67] offset:64
	v_pk_mul_f32 v[76:77], v[160:161], v[188:189]
	v_pk_mul_f32 v[78:79], v[162:163], v[190:191]
	v_cvt_pk_bf16_f32 v76, v76, v77
	v_cvt_pk_bf16_f32 v77, v78, v79
	global_store_dwordx2 v173, v[76:77], s[8:9] offset:32
	v_fmac_f32_e32 v82, v160, v160
	v_fmac_f32_e32 v82, v161, v161
	v_fmac_f32_e32 v82, v162, v162
	v_fmac_f32_e32 v82, v163, v163
	global_load_dwordx4 v[160:163], v164, s[98:99] offset:64 nt
	s_waitcnt vmcnt(21)
	v_pk_fma_f32 v[174:175], v[68:69], v[92:93], v[174:175]
	v_pk_fma_f32 v[176:177], v[70:71], v[94:95], v[176:177]
	global_store_dwordx4 v165, v[174:177], s[66:67] offset:512
	v_pk_mul_f32 v[68:69], v[174:175], v[192:193]
	v_pk_mul_f32 v[70:71], v[176:177], v[194:195]
	v_cvt_pk_bf16_f32 v68, v68, v69
	v_cvt_pk_bf16_f32 v69, v70, v71
	global_store_dwordx2 v173, v[68:69], s[8:9] offset:256
	v_fmac_f32_e32 v82, v174, v174
	v_fmac_f32_e32 v82, v175, v175
	v_fmac_f32_e32 v82, v176, v176
	v_fmac_f32_e32 v82, v177, v177
	global_load_dwordx4 v[174:177], v164, s[98:99] offset:512 nt
	s_waitcnt vmcnt(21)
	v_pk_fma_f32 v[178:179], v[64:65], v[96:97], v[178:179]
	v_pk_fma_f32 v[180:181], v[66:67], v[98:99], v[180:181]
	global_store_dwordx4 v165, v[178:181], s[66:67] offset:576
	v_pk_mul_f32 v[64:65], v[178:179], v[196:197]
	v_pk_mul_f32 v[66:67], v[180:181], v[198:199]
	v_cvt_pk_bf16_f32 v64, v64, v65
	v_cvt_pk_bf16_f32 v65, v66, v67
	global_store_dwordx2 v173, v[64:65], s[8:9] offset:288
	v_fmac_f32_e32 v82, v178, v178
	v_fmac_f32_e32 v82, v179, v179
	v_fmac_f32_e32 v82, v180, v180
	v_fmac_f32_e32 v82, v181, v181
	v_add_u32_e32 v165, 0xa0000, v165
	v_lshrrev_b32_e32 v173, 1, v165
	global_load_dwordx4 v[178:181], v164, s[98:99] offset:576 nt
	v_add_u32_e32 v164, 0x20000, v164
	s_waitcnt vmcnt(21)
	v_pk_fma_f32 v[200:201], v[60:61], v[72:73], v[200:201]
	v_pk_fma_f32 v[202:203], v[62:63], v[74:75], v[202:203]
	global_store_dwordx4 v165, v[200:203], s[66:67]
	v_pk_mul_f32 v[60:61], v[200:201], v[182:183]
	v_pk_mul_f32 v[62:63], v[202:203], v[184:185]
	v_cvt_pk_bf16_f32 v60, v60, v61
	v_cvt_pk_bf16_f32 v61, v62, v63
	global_store_dwordx2 v173, v[60:61], s[8:9]
	v_mul_f32_e32 v62, v200, v200
	v_fmac_f32_e32 v62, v201, v201
	v_fmac_f32_e32 v62, v202, v202
	v_fmac_f32_e32 v62, v203, v203
	global_load_dwordx4 v[200:203], v164, s[98:99] nt
	s_waitcnt vmcnt(21)
	v_pk_fma_f32 v[204:205], v[56:57], v[84:85], v[204:205]
	v_pk_fma_f32 v[206:207], v[58:59], v[86:87], v[206:207]
	global_store_dwordx4 v165, v[204:207], s[66:67] offset:64
	v_pk_mul_f32 v[56:57], v[204:205], v[188:189]
	v_pk_mul_f32 v[58:59], v[206:207], v[190:191]
	v_cvt_pk_bf16_f32 v56, v56, v57
	v_cvt_pk_bf16_f32 v57, v58, v59
	global_store_dwordx2 v173, v[56:57], s[8:9] offset:32
	v_fmac_f32_e32 v62, v204, v204
	v_fmac_f32_e32 v62, v205, v205
	v_fmac_f32_e32 v62, v206, v206
	v_fmac_f32_e32 v62, v207, v207
	global_load_dwordx4 v[204:207], v164, s[98:99] offset:64 nt
	s_waitcnt vmcnt(21)
	v_pk_fma_f32 v[208:209], v[52:53], v[92:93], v[208:209]
	v_pk_fma_f32 v[210:211], v[54:55], v[94:95], v[210:211]
	global_store_dwordx4 v165, v[208:211], s[66:67] offset:512
	v_pk_mul_f32 v[52:53], v[208:209], v[192:193]
	v_pk_mul_f32 v[54:55], v[210:211], v[194:195]
	v_cvt_pk_bf16_f32 v52, v52, v53
	v_cvt_pk_bf16_f32 v53, v54, v55
	global_store_dwordx2 v173, v[52:53], s[8:9] offset:256
	v_fmac_f32_e32 v62, v208, v208
	v_fmac_f32_e32 v62, v209, v209
	v_fmac_f32_e32 v62, v210, v210
	v_fmac_f32_e32 v62, v211, v211
	global_load_dwordx4 v[208:211], v164, s[98:99] offset:512 nt
	s_waitcnt vmcnt(21)
	v_pk_fma_f32 v[212:213], v[48:49], v[96:97], v[212:213]
	v_pk_fma_f32 v[214:215], v[50:51], v[98:99], v[214:215]
	global_store_dwordx4 v165, v[212:215], s[66:67] offset:576
	v_pk_mul_f32 v[48:49], v[212:213], v[196:197]
	v_pk_mul_f32 v[50:51], v[214:215], v[198:199]
	v_cvt_pk_bf16_f32 v48, v48, v49
	v_cvt_pk_bf16_f32 v49, v50, v51
	global_store_dwordx2 v173, v[48:49], s[8:9] offset:288
	v_fmac_f32_e32 v62, v212, v212
	v_fmac_f32_e32 v62, v213, v213
	v_fmac_f32_e32 v62, v214, v214
	v_fmac_f32_e32 v62, v215, v215
	v_add_u32_e32 v165, 0x20000, v165
	v_lshrrev_b32_e32 v173, 1, v165
	global_load_dwordx4 v[212:215], v164, s[98:99] offset:576 nt
	v_add_u32_e32 v164, 0x20000, v164
	s_waitcnt vmcnt(21)
	v_pk_fma_f32 v[156:157], v[44:45], v[72:73], v[156:157]
	v_pk_fma_f32 v[158:159], v[46:47], v[74:75], v[158:159]
	global_store_dwordx4 v165, v[156:159], s[66:67]
	v_pk_mul_f32 v[44:45], v[156:157], v[182:183]
	v_pk_mul_f32 v[46:47], v[158:159], v[184:185]
	v_cvt_pk_bf16_f32 v44, v44, v45
	v_cvt_pk_bf16_f32 v45, v46, v47
	global_store_dwordx2 v173, v[44:45], s[8:9]
	v_mul_f32_e32 v46, v156, v156
	v_fmac_f32_e32 v46, v157, v157
	v_fmac_f32_e32 v46, v158, v158
	v_fmac_f32_e32 v46, v159, v159
	global_load_dwordx4 v[156:159], v164, s[98:99] nt
	s_waitcnt vmcnt(21)
	v_pk_fma_f32 v[160:161], v[40:41], v[84:85], v[160:161]
	v_pk_fma_f32 v[162:163], v[42:43], v[86:87], v[162:163]
	global_store_dwordx4 v165, v[160:163], s[66:67] offset:64
	v_pk_mul_f32 v[40:41], v[160:161], v[188:189]
	v_pk_mul_f32 v[42:43], v[162:163], v[190:191]
	v_cvt_pk_bf16_f32 v40, v40, v41
	v_cvt_pk_bf16_f32 v41, v42, v43
	global_store_dwordx2 v173, v[40:41], s[8:9] offset:32
	v_fmac_f32_e32 v46, v160, v160
	v_fmac_f32_e32 v46, v161, v161
	v_fmac_f32_e32 v46, v162, v162
	v_fmac_f32_e32 v46, v163, v163
	global_load_dwordx4 v[160:163], v164, s[98:99] offset:64 nt
	s_waitcnt vmcnt(21)
; __device__ __forceinline__ unsigned cvt_pk_bf16(float lo, float hi) { unsigned r; asm volatile("v_cvt_pk_bf16_f32 %0, %1, %2" : "=v"(r) : "v"(lo), "v"(hi)); return r; }
;     __device__ __forceinline__ void operator()(const f32x4 (&acc)[2][2][4][2], const Unit& u, int wr, int wc, int fr, int fq) const {
;     ...
;             for (int m = 0; m < 4; ++m) { const int row = row0 + ai * HALF + m * 16; const size_t off = (size_t)row * 2048 + col0; float ss = 0.f;
; #pragma unroll
;                 for (int bj = 0; bj < 2; ++bj)
; #pragma unroll
;                     for (int n = 0; n < 2; ++n) { const f32x4 bs = __builtin_nontemporal_load((const f32x4*)(base + off + bj * HALF + n * 16)); const f32x4 x1 = bs + gv[bj][n] * acc[ai][bj][m][n];
;                         *(f32x4*)(out + off + bj * HALF + n * 16) = x1; ss += (x1.x * x1.x + x1.y * x1.y) + (x1.z * x1.z + x1.w * x1.w);
;                         const f32x4 hh = x1 * Gv[bj][n]; u32x2 w; w.x = cvt_pk_bf16(hh.x, hh.y); w.y = cvt_pk_bf16(hh.z, hh.w); *(u32x2*)(A2 + off + bj * HALF + n * 16) = w; }
	v_pk_fma_f32 v[174:175], v[36:37], v[92:93], v[174:175]
	v_pk_fma_f32 v[176:177], v[38:39], v[94:95], v[176:177]
	global_store_dwordx4 v165, v[174:177], s[66:67] offset:512
	v_pk_mul_f32 v[36:37], v[174:175], v[192:193]
	v_pk_mul_f32 v[38:39], v[176:177], v[194:195]
	v_cvt_pk_bf16_f32 v36, v36, v37
	v_cvt_pk_bf16_f32 v37, v38, v39
	global_store_dwordx2 v173, v[36:37], s[8:9] offset:256
	v_fmac_f32_e32 v46, v174, v174
	v_fmac_f32_e32 v46, v175, v175
	v_fmac_f32_e32 v46, v176, v176
	v_fmac_f32_e32 v46, v177, v177
	global_load_dwordx4 v[174:177], v164, s[98:99] offset:512 nt
	s_waitcnt vmcnt(21)
	v_pk_fma_f32 v[178:179], v[32:33], v[96:97], v[178:179]
	v_pk_fma_f32 v[180:181], v[34:35], v[98:99], v[180:181]
	global_store_dwordx4 v165, v[178:181], s[66:67] offset:576
	v_pk_mul_f32 v[32:33], v[178:179], v[196:197]
	v_pk_mul_f32 v[34:35], v[180:181], v[198:199]
	v_cvt_pk_bf16_f32 v32, v32, v33
	v_cvt_pk_bf16_f32 v33, v34, v35
	global_store_dwordx2 v173, v[32:33], s[8:9] offset:288
	v_fmac_f32_e32 v46, v178, v178
	v_fmac_f32_e32 v46, v179, v179
	v_fmac_f32_e32 v46, v180, v180
	v_fmac_f32_e32 v46, v181, v181
	v_add_u32_e32 v165, 0x20000, v165
	v_lshrrev_b32_e32 v173, 1, v165
	global_load_dwordx4 v[178:181], v164, s[98:99] offset:576 nt
	s_waitcnt vmcnt(21)
	v_pk_fma_f32 v[200:201], v[28:29], v[72:73], v[200:201]
	v_pk_fma_f32 v[202:203], v[30:31], v[74:75], v[202:203]
	global_store_dwordx4 v165, v[200:203], s[66:67]
	v_pk_mul_f32 v[28:29], v[200:201], v[182:183]
	v_pk_mul_f32 v[30:31], v[202:203], v[184:185]
	v_cvt_pk_bf16_f32 v28, v28, v29
	v_cvt_pk_bf16_f32 v29, v30, v31
	global_store_dwordx2 v173, v[28:29], s[8:9]
	v_mul_f32_e32 v30, v200, v200
	v_fmac_f32_e32 v30, v201, v201
	v_fmac_f32_e32 v30, v202, v202
	v_fmac_f32_e32 v30, v203, v203
	s_waitcnt vmcnt(20)
	v_pk_fma_f32 v[204:205], v[24:25], v[84:85], v[204:205]
	v_pk_fma_f32 v[206:207], v[26:27], v[86:87], v[206:207]
	global_store_dwordx4 v165, v[204:207], s[66:67] offset:64
	v_pk_mul_f32 v[24:25], v[204:205], v[188:189]
	v_pk_mul_f32 v[26:27], v[206:207], v[190:191]
	v_cvt_pk_bf16_f32 v24, v24, v25
	v_cvt_pk_bf16_f32 v25, v26, v27
	global_store_dwordx2 v173, v[24:25], s[8:9] offset:32
	v_fmac_f32_e32 v30, v204, v204
	v_fmac_f32_e32 v30, v205, v205
	v_fmac_f32_e32 v30, v206, v206
	v_fmac_f32_e32 v30, v207, v207
	s_waitcnt vmcnt(19)
	v_pk_fma_f32 v[208:209], v[20:21], v[92:93], v[208:209]
	v_pk_fma_f32 v[210:211], v[22:23], v[94:95], v[210:211]
	global_store_dwordx4 v165, v[208:211], s[66:67] offset:512
	v_pk_mul_f32 v[20:21], v[208:209], v[192:193]
	v_pk_mul_f32 v[22:23], v[210:211], v[194:195]
	v_cvt_pk_bf16_f32 v20, v20, v21
	v_cvt_pk_bf16_f32 v21, v22, v23
	global_store_dwordx2 v173, v[20:21], s[8:9] offset:256
	v_fmac_f32_e32 v30, v208, v208
	v_fmac_f32_e32 v30, v209, v209
	v_fmac_f32_e32 v30, v210, v210
	v_fmac_f32_e32 v30, v211, v211
	s_waitcnt vmcnt(18)
	v_pk_fma_f32 v[212:213], v[16:17], v[96:97], v[212:213]
	v_pk_fma_f32 v[214:215], v[18:19], v[98:99], v[214:215]
	global_store_dwordx4 v165, v[212:215], s[66:67] offset:576
	v_pk_mul_f32 v[16:17], v[212:213], v[196:197]
	v_pk_mul_f32 v[18:19], v[214:215], v[198:199]
	v_cvt_pk_bf16_f32 v16, v16, v17
	v_cvt_pk_bf16_f32 v17, v18, v19
	global_store_dwordx2 v173, v[16:17], s[8:9] offset:288
	v_fmac_f32_e32 v30, v212, v212
	v_fmac_f32_e32 v30, v213, v213
	v_fmac_f32_e32 v30, v214, v214
	v_fmac_f32_e32 v30, v215, v215
	v_add_u32_e32 v165, 0x20000, v165
	v_lshrrev_b32_e32 v173, 1, v165
	s_waitcnt vmcnt(17)
; #define PG8_BAR __builtin_amdgcn_s_barrier()
;     __device__ __forceinline__ void operator()(const f32x4 (&acc)[2][2][4][2], const Unit& u, int wr, int wc, int fr, int fq) const {
;     ...
;                 ss += __shfl_xor(ss, 16); ss += __shfl_xor(ss, 32);
;                 if (fq == 0) prow[row] = ss; }
; template <class Epi, class Sched, bool ALIGN_EPI = false, bool SP2 = false>
; __device__ __forceinline__ void gemm_phase(PG8_LAS unsigned char* lds, const Gemm g, const Sched& S, const Epi& E) {
;     ...
;         if (!has_next) break;
; #pragma unroll
;         for (int a = 0; a < 2; ++a)
; #pragma unroll
;             for (int b = 0; b < 2; ++b)
; #pragma unroll
;                 for (int m = 0; m < 4; ++m)
; #pragma unroll
;                     for (int n = 0; n < 2; ++n) acc[a][b][m][n] = (f32x4){0.f, 0.f, 0.f, 0.f};
;         cur = nxt; cA = nA; cB = nB; ++ui;
;         if constexpr (ALIGN_EPI) { if (wr == 1) PG8_BAR; }
	v_pk_fma_f32 v[156:157], v[12:13], v[72:73], v[156:157]
	v_pk_fma_f32 v[158:159], v[14:15], v[74:75], v[158:159]
	global_store_dwordx4 v165, v[156:159], s[66:67]
	v_pk_mul_f32 v[12:13], v[156:157], v[182:183]
	v_pk_mul_f32 v[14:15], v[158:159], v[184:185]
	v_cvt_pk_bf16_f32 v12, v12, v13
	v_cvt_pk_bf16_f32 v13, v14, v15
	global_store_dwordx2 v173, v[12:13], s[8:9]
	v_mul_f32_e32 v14, v156, v156
	v_fmac_f32_e32 v14, v157, v157
	v_fmac_f32_e32 v14, v158, v158
	v_fmac_f32_e32 v14, v159, v159
	s_waitcnt vmcnt(16)
	v_pk_fma_f32 v[160:161], v[8:9], v[84:85], v[160:161]
	v_pk_fma_f32 v[162:163], v[10:11], v[86:87], v[162:163]
	global_store_dwordx4 v165, v[160:163], s[66:67] offset:64
	v_pk_mul_f32 v[8:9], v[160:161], v[188:189]
	v_pk_mul_f32 v[10:11], v[162:163], v[190:191]
	v_cvt_pk_bf16_f32 v8, v8, v9
	v_cvt_pk_bf16_f32 v9, v10, v11
	global_store_dwordx2 v173, v[8:9], s[8:9] offset:32
	v_fmac_f32_e32 v14, v160, v160
	v_fmac_f32_e32 v14, v161, v161
	v_fmac_f32_e32 v14, v162, v162
	v_fmac_f32_e32 v14, v163, v163
	s_waitcnt vmcnt(15)
	v_pk_fma_f32 v[174:175], v[4:5], v[92:93], v[174:175]
	v_pk_fma_f32 v[176:177], v[6:7], v[94:95], v[176:177]
	global_store_dwordx4 v165, v[174:177], s[66:67] offset:512
	v_pk_mul_f32 v[4:5], v[174:175], v[192:193]
	v_pk_mul_f32 v[6:7], v[176:177], v[194:195]
	v_cvt_pk_bf16_f32 v4, v4, v5
	v_cvt_pk_bf16_f32 v5, v6, v7
	global_store_dwordx2 v173, v[4:5], s[8:9] offset:256
	v_fmac_f32_e32 v14, v174, v174
	v_fmac_f32_e32 v14, v175, v175
	v_fmac_f32_e32 v14, v176, v176
	v_fmac_f32_e32 v14, v177, v177
	s_waitcnt vmcnt(14)
	v_pk_fma_f32 v[178:179], v[0:1], v[96:97], v[178:179]
	v_pk_fma_f32 v[180:181], v[2:3], v[98:99], v[180:181]
	global_store_dwordx4 v165, v[178:181], s[66:67] offset:576
	v_pk_mul_f32 v[0:1], v[178:179], v[196:197]
	v_pk_mul_f32 v[2:3], v[180:181], v[198:199]
	v_cvt_pk_bf16_f32 v0, v0, v1
	v_cvt_pk_bf16_f32 v1, v2, v3
	global_store_dwordx2 v173, v[0:1], s[8:9] offset:288
	v_fmac_f32_e32 v14, v178, v178
	v_fmac_f32_e32 v14, v179, v179
	v_fmac_f32_e32 v14, v180, v180
	v_fmac_f32_e32 v14, v181, v181
	ds_bpermute_b32 v143, v216, v142
	ds_bpermute_b32 v127, v216, v126
	ds_bpermute_b32 v111, v216, v110
	ds_bpermute_b32 v83, v216, v82
	ds_bpermute_b32 v63, v216, v62
	ds_bpermute_b32 v47, v216, v46
	ds_bpermute_b32 v31, v216, v30
	ds_bpermute_b32 v15, v216, v14
	s_waitcnt lgkmcnt(0)
	v_add_f32_e32 v142, v142, v143
	v_add_f32_e32 v126, v126, v127
	v_add_f32_e32 v110, v110, v111
	v_add_f32_e32 v82, v82, v83
	v_add_f32_e32 v62, v62, v63
	v_add_f32_e32 v46, v46, v47
	v_add_f32_e32 v30, v30, v31
	v_add_f32_e32 v14, v14, v15
	ds_bpermute_b32 v143, v217, v142
	ds_bpermute_b32 v127, v217, v126
	ds_bpermute_b32 v111, v217, v110
	ds_bpermute_b32 v83, v217, v82
	ds_bpermute_b32 v63, v217, v62
	ds_bpermute_b32 v47, v217, v46
	ds_bpermute_b32 v31, v217, v30
	ds_bpermute_b32 v15, v217, v14
	s_lshl_b32 s25, s34, 2
	s_or_b32 s25, s25, s47
	s_lshl_b32 s25, s25, 16
	v_lshl_add_u32 v164, s36, 8, v166
	v_lshl_add_u32 v164, v164, 2, s25
	s_waitcnt lgkmcnt(0)
	v_add_f32_e32 v142, v142, v143
	v_add_f32_e32 v126, v126, v127
	v_add_f32_e32 v110, v110, v111
	v_add_f32_e32 v82, v82, v83
	v_add_f32_e32 v62, v62, v63
	v_add_f32_e32 v46, v46, v47
	v_add_f32_e32 v30, v30, v31
	v_add_f32_e32 v14, v14, v15
	s_and_saveexec_b64 s[100:101], s[4:5]
	global_store_dword v164, v142, s[48:49]
	global_store_dword v164, v126, s[48:49] offset:64
	global_store_dword v164, v110, s[48:49] offset:128
	global_store_dword v164, v82, s[48:49] offset:192
	global_store_dword v164, v62, s[48:49] offset:512
	global_store_dword v164, v46, s[48:49] offset:576
	global_store_dword v164, v30, s[48:49] offset:640
	global_store_dword v164, v14, s[48:49] offset:704
	s_or_b64 exec, exec, s[100:101]
	s_andn2_b64 vcc, exec, s[6:7]
	s_mov_b64 s[6:7], -1
	s_cbranch_vccnz .LBB0_886
	s_andn2_b64 vcc, exec, s[10:11]
	s_cbranch_vccnz .LBB0_885
	s_barrier
	s_branch .LBB0_885

;     __device__ __forceinline__ void operator()(const f32x4 (&acc)[2][2][4][2], const Unit& u, int wr, int wc, int fr, int fq) const {
;         const int row0 = u.pm * BM + wr * 64 + fr, col0 = u.pn * BM + wc * 32 + 4 * fq, b = (u.pm * BM) >> 12;
;         f32x4 gv[2][2];
; #pragma unroll
;         for (int bj = 0; bj < 2; ++bj)
; #pragma unroll
;             for (int n = 0; n < 2; ++n) gv[bj][n] = *(const f32x4*)(gate + (size_t)b * 12288 + col0 + bj * HALF + n * 16);
; #pragma unroll
;         for (int ai = 0; ai < 2; ++ai)
; #pragma unroll
;             for (int m = 0; m < 4; ++m) { const size_t off = (size_t)(row0 + ai * HALF + m * 16) * 2048 + col0;
; #pragma unroll
;                 for (int bj = 0; bj < 2; ++bj)
; #pragma unroll
;                     for (int n = 0; n < 2; ++n) { const f32x4 bs = __builtin_nontemporal_load((const f32x4*)(base + off + bj * HALF + n * 16));
;                         *(f32x4*)(out + off + bj * HALF + n * 16) = bs + gv[bj][n] * acc[ai][bj][m][n]; } }
.LBB0_1074:
	s_ashr_i32 s17, s24, 4
	v_lshl_add_u32 v160, s24, 8, v162
	v_lshl_or_b32 v64, s25, 8, v164
	s_mul_hi_i32 s19, s17, 0xc000
	s_mul_i32 s17, s17, 0xc000
	v_ashrrev_i32_e32 v161, 31, v160
	s_add_u32 s26, s40, s17
	v_ashrrev_i32_e32 v65, 31, v64
	v_lshlrev_b64 v[156:157], 13, v[160:161]
	s_addc_u32 s27, s41, s19
	v_lshlrev_b64 v[158:159], 2, v[64:65]
	v_lshl_add_u64 v[156:157], s[66:67], 0, v[156:157]
	v_lshl_add_u64 v[64:65], s[26:27], 0, v[158:159]
	v_lshl_add_u64 v[156:157], v[156:157], 0, v[158:159]
	global_load_dwordx4 v[128:131], v[64:65], off
	global_load_dwordx4 v[116:119], v[64:65], off offset:64
	global_load_dwordx4 v[108:111], v[64:65], off offset:512
	s_nop 0
	global_load_dwordx4 v[64:67], v[64:65], off offset:576
	s_mov_b64 s[24:25], -1
	s_mov_b64 s[98:99], 0x20000
	s_mov_b64 s[100:101], 0xa0000
	v_mov_b64_e32 v[158:159], v[156:157]
	global_load_dwordx4 v[168:171], v[158:159], off nt
	global_load_dwordx4 v[172:175], v[158:159], off offset:64 nt
	global_load_dwordx4 v[176:179], v[158:159], off offset:512 nt
	global_load_dwordx4 v[180:183], v[158:159], off offset:576 nt
	v_lshl_add_u64 v[158:159], v[158:159], 0, s[98:99]
	global_load_dwordx4 v[184:187], v[158:159], off nt
	global_load_dwordx4 v[188:191], v[158:159], off offset:64 nt
	global_load_dwordx4 v[192:195], v[158:159], off offset:512 nt
	global_load_dwordx4 v[196:199], v[158:159], off offset:576 nt
	v_lshl_add_u64 v[158:159], v[158:159], 0, s[98:99]
	global_load_dwordx4 v[200:203], v[158:159], off nt
	global_load_dwordx4 v[204:207], v[158:159], off offset:64 nt
	global_load_dwordx4 v[208:211], v[158:159], off offset:512 nt
	s_and_b64 vcc, exec, s[6:7]
	s_cbranch_vccz .Lalignmv_p8
	s_barrier
.Lalignmv_p8:
	s_waitcnt vmcnt(10)
	v_pk_fma_f32 v[142:143], v[142:143], v[130:131], v[170:171]
	v_pk_fma_f32 v[140:141], v[140:141], v[128:129], v[168:169]
	global_store_dwordx4 v[156:157], v[140:143], off
	global_load_dwordx4 v[168:171], v[158:159], off offset:576 nt
	v_lshl_add_u64 v[158:159], v[158:159], 0, s[98:99]
	s_waitcnt vmcnt(11)
	v_pk_fma_f32 v[138:139], v[138:139], v[118:119], v[174:175]
	v_pk_fma_f32 v[136:137], v[136:137], v[116:117], v[172:173]
	global_store_dwordx4 v[156:157], v[136:139], off offset:64
	global_load_dwordx4 v[172:175], v[158:159], off nt
	s_waitcnt vmcnt(12)
	v_pk_fma_f32 v[134:135], v[134:135], v[110:111], v[178:179]
	v_pk_fma_f32 v[132:133], v[132:133], v[108:109], v[176:177]
	global_store_dwordx4 v[156:157], v[132:135], off offset:512
	global_load_dwordx4 v[176:179], v[158:159], off offset:64 nt
	s_waitcnt vmcnt(13)
	v_pk_fma_f32 v[126:127], v[126:127], v[66:67], v[182:183]
	v_pk_fma_f32 v[124:125], v[124:125], v[64:65], v[180:181]
	global_store_dwordx4 v[156:157], v[124:127], off offset:576
	v_lshl_add_u64 v[156:157], v[156:157], 0, s[98:99]
	global_load_dwordx4 v[180:183], v[158:159], off offset:512 nt
	s_waitcnt vmcnt(14)
	v_pk_fma_f32 v[122:123], v[122:123], v[130:131], v[186:187]
	v_pk_fma_f32 v[120:121], v[120:121], v[128:129], v[184:185]
	global_store_dwordx4 v[156:157], v[120:123], off
	global_load_dwordx4 v[184:187], v[158:159], off offset:576 nt
	v_lshl_add_u64 v[158:159], v[158:159], 0, s[100:101]
	s_waitcnt vmcnt(15)
	v_pk_fma_f32 v[114:115], v[114:115], v[118:119], v[190:191]
	v_pk_fma_f32 v[112:113], v[112:113], v[116:117], v[188:189]
	global_store_dwordx4 v[156:157], v[112:115], off offset:64
	global_load_dwordx4 v[188:191], v[158:159], off nt
	s_waitcnt vmcnt(16)
	v_pk_fma_f32 v[106:107], v[106:107], v[110:111], v[194:195]
	v_pk_fma_f32 v[104:105], v[104:105], v[108:109], v[192:193]
	global_store_dwordx4 v[156:157], v[104:107], off offset:512
	global_load_dwordx4 v[192:195], v[158:159], off offset:64 nt
	s_waitcnt vmcnt(17)
	v_pk_fma_f32 v[102:103], v[102:103], v[66:67], v[198:199]
	v_pk_fma_f32 v[100:101], v[100:101], v[64:65], v[196:197]
	global_store_dwordx4 v[156:157], v[100:103], off offset:576
	v_lshl_add_u64 v[156:157], v[156:157], 0, s[98:99]
	global_load_dwordx4 v[196:199], v[158:159], off offset:512 nt
	s_waitcnt vmcnt(18)
	v_pk_fma_f32 v[98:99], v[98:99], v[130:131], v[202:203]
	v_pk_fma_f32 v[96:97], v[96:97], v[128:129], v[200:201]
	global_store_dwordx4 v[156:157], v[96:99], off
	global_load_dwordx4 v[200:203], v[158:159], off offset:576 nt
	v_lshl_add_u64 v[158:159], v[158:159], 0, s[98:99]
	s_waitcnt vmcnt(19)
	v_pk_fma_f32 v[94:95], v[94:95], v[118:119], v[206:207]
	v_pk_fma_f32 v[92:93], v[92:93], v[116:117], v[204:205]
	global_store_dwordx4 v[156:157], v[92:95], off offset:64
	global_load_dwordx4 v[204:207], v[158:159], off nt
	s_waitcnt vmcnt(20)
	v_pk_fma_f32 v[90:91], v[90:91], v[110:111], v[210:211]
	v_pk_fma_f32 v[88:89], v[88:89], v[108:109], v[208:209]
	global_store_dwordx4 v[156:157], v[88:91], off offset:512
	global_load_dwordx4 v[208:211], v[158:159], off offset:64 nt
	s_waitcnt vmcnt(20)
; #define PG8_BAR __builtin_amdgcn_s_barrier()
;     __device__ __forceinline__ void operator()(const f32x4 (&acc)[2][2][4][2], const Unit& u, int wr, int wc, int fr, int fq) const {
;     ...
;             for (int m = 0; m < 4; ++m) { const size_t off = (size_t)(row0 + ai * HALF + m * 16) * 2048 + col0;
; #pragma unroll
;                 for (int bj = 0; bj < 2; ++bj)
; #pragma unroll
;                     for (int n = 0; n < 2; ++n) { const f32x4 bs = __builtin_nontemporal_load((const f32x4*)(base + off + bj * HALF + n * 16));
;                         *(f32x4*)(out + off + bj * HALF + n * 16) = bs + gv[bj][n] * acc[ai][bj][m][n]; } }
; template <class Epi, class Sched, bool ALIGN_EPI = false, bool SP2 = false>
; __device__ __forceinline__ void gemm_phase(PG8_LAS unsigned char* lds, const Gemm g, const Sched& S, const Epi& E) {
;     ...
;         if (!has_next) break;
; #pragma unroll
;         for (int a = 0; a < 2; ++a)
; #pragma unroll
;             for (int b = 0; b < 2; ++b)
; #pragma unroll
;                 for (int m = 0; m < 4; ++m)
; #pragma unroll
;                     for (int n = 0; n < 2; ++n) acc[a][b][m][n] = (f32x4){0.f, 0.f, 0.f, 0.f};
;         cur = nxt; cA = nA; cB = nB; ++ui;
;         if constexpr (ALIGN_EPI) { if (wr == 1) PG8_BAR; }
	v_pk_fma_f32 v[86:87], v[86:87], v[66:67], v[170:171]
	v_pk_fma_f32 v[84:85], v[84:85], v[64:65], v[168:169]
	global_store_dwordx4 v[156:157], v[84:87], off offset:576
	v_lshl_add_u64 v[156:157], v[156:157], 0, s[98:99]
	global_load_dwordx4 v[168:171], v[158:159], off offset:512 nt
	s_waitcnt vmcnt(20)
	v_pk_fma_f32 v[82:83], v[82:83], v[130:131], v[174:175]
	v_pk_fma_f32 v[80:81], v[80:81], v[128:129], v[172:173]
	global_store_dwordx4 v[156:157], v[80:83], off
	global_load_dwordx4 v[172:175], v[158:159], off offset:576 nt
	v_lshl_add_u64 v[158:159], v[158:159], 0, s[98:99]
	s_waitcnt vmcnt(20)
	v_pk_fma_f32 v[78:79], v[78:79], v[118:119], v[178:179]
	v_pk_fma_f32 v[76:77], v[76:77], v[116:117], v[176:177]
	global_store_dwordx4 v[156:157], v[76:79], off offset:64
	global_load_dwordx4 v[176:179], v[158:159], off nt
	s_waitcnt vmcnt(20)
	v_pk_fma_f32 v[74:75], v[74:75], v[110:111], v[182:183]
	v_pk_fma_f32 v[72:73], v[72:73], v[108:109], v[180:181]
	global_store_dwordx4 v[156:157], v[72:75], off offset:512
	global_load_dwordx4 v[180:183], v[158:159], off offset:64 nt
	s_waitcnt vmcnt(20)
	v_pk_fma_f32 v[70:71], v[70:71], v[66:67], v[186:187]
	v_pk_fma_f32 v[68:69], v[68:69], v[64:65], v[184:185]
	global_store_dwordx4 v[156:157], v[68:71], off offset:576
	v_lshl_add_u64 v[156:157], v[156:157], 0, s[100:101]
	global_load_dwordx4 v[184:187], v[158:159], off offset:512 nt
	s_waitcnt vmcnt(20)
	v_pk_fma_f32 v[62:63], v[62:63], v[130:131], v[190:191]
	v_pk_fma_f32 v[60:61], v[60:61], v[128:129], v[188:189]
	global_store_dwordx4 v[156:157], v[60:63], off
	global_load_dwordx4 v[188:191], v[158:159], off offset:576 nt
	v_lshl_add_u64 v[158:159], v[158:159], 0, s[98:99]
	s_waitcnt vmcnt(20)
	v_pk_fma_f32 v[58:59], v[58:59], v[118:119], v[194:195]
	v_pk_fma_f32 v[56:57], v[56:57], v[116:117], v[192:193]
	global_store_dwordx4 v[156:157], v[56:59], off offset:64
	global_load_dwordx4 v[192:195], v[158:159], off nt
	s_waitcnt vmcnt(20)
	v_pk_fma_f32 v[54:55], v[54:55], v[110:111], v[198:199]
	v_pk_fma_f32 v[52:53], v[52:53], v[108:109], v[196:197]
	global_store_dwordx4 v[156:157], v[52:55], off offset:512
	global_load_dwordx4 v[196:199], v[158:159], off offset:64 nt
	s_waitcnt vmcnt(20)
	v_pk_fma_f32 v[50:51], v[50:51], v[66:67], v[202:203]
	v_pk_fma_f32 v[48:49], v[48:49], v[64:65], v[200:201]
	global_store_dwordx4 v[156:157], v[48:51], off offset:576
	v_lshl_add_u64 v[156:157], v[156:157], 0, s[98:99]
	global_load_dwordx4 v[200:203], v[158:159], off offset:512 nt
	s_waitcnt vmcnt(20)
	v_pk_fma_f32 v[46:47], v[46:47], v[130:131], v[206:207]
	v_pk_fma_f32 v[44:45], v[44:45], v[128:129], v[204:205]
	global_store_dwordx4 v[156:157], v[44:47], off
	global_load_dwordx4 v[204:207], v[158:159], off offset:576 nt
	s_waitcnt vmcnt(20)
	v_pk_fma_f32 v[42:43], v[42:43], v[118:119], v[210:211]
	v_pk_fma_f32 v[40:41], v[40:41], v[116:117], v[208:209]
	global_store_dwordx4 v[156:157], v[40:43], off offset:64
	s_waitcnt vmcnt(19)
	v_pk_fma_f32 v[38:39], v[38:39], v[110:111], v[170:171]
	v_pk_fma_f32 v[36:37], v[36:37], v[108:109], v[168:169]
	global_store_dwordx4 v[156:157], v[36:39], off offset:512
	s_waitcnt vmcnt(18)
	v_pk_fma_f32 v[34:35], v[34:35], v[66:67], v[174:175]
	v_pk_fma_f32 v[32:33], v[32:33], v[64:65], v[172:173]
	global_store_dwordx4 v[156:157], v[32:35], off offset:576
	v_lshl_add_u64 v[156:157], v[156:157], 0, s[98:99]
	s_waitcnt vmcnt(17)
	v_pk_fma_f32 v[30:31], v[30:31], v[130:131], v[178:179]
	v_pk_fma_f32 v[28:29], v[28:29], v[128:129], v[176:177]
	global_store_dwordx4 v[156:157], v[28:31], off
	s_waitcnt vmcnt(16)
	v_pk_fma_f32 v[26:27], v[26:27], v[118:119], v[182:183]
	v_pk_fma_f32 v[24:25], v[24:25], v[116:117], v[180:181]
	global_store_dwordx4 v[156:157], v[24:27], off offset:64
	s_waitcnt vmcnt(15)
	v_pk_fma_f32 v[22:23], v[22:23], v[110:111], v[186:187]
	v_pk_fma_f32 v[20:21], v[20:21], v[108:109], v[184:185]
	global_store_dwordx4 v[156:157], v[20:23], off offset:512
	s_waitcnt vmcnt(14)
	v_pk_fma_f32 v[18:19], v[18:19], v[66:67], v[190:191]
	v_pk_fma_f32 v[16:17], v[16:17], v[64:65], v[188:189]
	global_store_dwordx4 v[156:157], v[16:19], off offset:576
	v_lshl_add_u64 v[156:157], v[156:157], 0, s[98:99]
	s_waitcnt vmcnt(13)
	v_pk_fma_f32 v[14:15], v[14:15], v[130:131], v[194:195]
	v_pk_fma_f32 v[12:13], v[12:13], v[128:129], v[192:193]
	global_store_dwordx4 v[156:157], v[12:15], off
	s_waitcnt vmcnt(12)
	v_pk_fma_f32 v[10:11], v[10:11], v[118:119], v[198:199]
	v_pk_fma_f32 v[8:9], v[8:9], v[116:117], v[196:197]
	global_store_dwordx4 v[156:157], v[8:11], off offset:64
	s_waitcnt vmcnt(11)
	v_pk_fma_f32 v[6:7], v[6:7], v[110:111], v[202:203]
	v_pk_fma_f32 v[4:5], v[4:5], v[108:109], v[200:201]
	global_store_dwordx4 v[156:157], v[4:7], off offset:512
	s_waitcnt vmcnt(10)
	v_pk_fma_f32 v[2:3], v[2:3], v[66:67], v[206:207]
	v_pk_fma_f32 v[0:1], v[0:1], v[64:65], v[204:205]
	global_store_dwordx4 v[156:157], v[0:3], off offset:576
	s_andn2_b64 vcc, exec, s[0:1]
	s_cbranch_vccnz .LBB0_1063
	s_andn2_b64 vcc, exec, s[2:3]
	s_cbranch_vccnz .LBB0_1062
	s_barrier
	s_branch .LBB0_1062
